# loop-edge edit: middle K iterations take a short back edge (one compare, one taken branch) instead of exit test + pre-issue test + 3-way dispatch
# speedup vs baseline: 1.0194x; 1.0194x over previous
.LBB0_142:
	s_cmp_eq_u32 s61, -2
	s_cbranch_scc1 .Lc0s_first
	s_cmp_eq_u32 s61, 28
	s_cbranch_scc0 .Lc0s_norm
	s_cmp_eq_u64 s[4:5], 0
	s_cbranch_scc1 .Lc0s_final
	s_branch .Lc0s_norm

.Lc0s_tail:
	s_add_i32 s61, s61, 2
	s_addk_i32 s58, 0x100
	s_addk_i32 s60, 0x100
	s_cmp_lt_u32 s61, 28
	s_cbranch_scc1 .Lc0s_mid
	s_cmp_gt_u32 s61, 29
	s_cbranch_scc1 .LBB0_145

.LBB0_162:
	s_cmp_eq_u32 s54, -2
	s_cbranch_scc1 .Lc0b_first
	s_cmp_eq_u32 s54, 28
	s_cbranch_scc0 .Lc0b_norm
	s_cmp_eq_u64 s[4:5], 0
	s_cbranch_scc1 .Lc0b_final
	s_branch .Lc0b_norm

.Lc0b_tail:
	s_add_i32 s54, s54, 2
	s_addk_i32 s52, 0x100
	s_addk_i32 s53, 0x100
	s_cmp_lt_u32 s54, 28
	s_cbranch_scc1 .Lc0b_mid
	s_cmp_gt_u32 s54, 29
	s_cbranch_scc1 .LBB0_165

.LBB0_382:
	s_cmp_eq_u32 s78, 0
	s_cbranch_scc1 .Lc0r_first
	s_cmp_eq_u32 s78, s52
	s_cbranch_scc0 .Lc0r_norm
	s_cmp_eq_u64 s[4:5], 0
	s_cbranch_scc1 .Lc0r_final
	s_branch .Lc0r_norm

.Lc0r_tail:
	s_add_i32 s78, s78, 2
	s_addk_i32 s64, 0x100
	s_addk_i32 s65, 0x100
	s_cmp_lt_u32 s78, s52
	s_cbranch_scc1 .Lc0r_mid
	s_cmp_ge_u32 s78, s47
	s_cbranch_scc1 .LBB0_385
